# K-loop back edge: loop-carried pointer increments hoisted above the closing barrier (7.11 partial)
# baseline (speedup 1.0000x reference)
.Lfm2_done:
	s_add_i32 s34, s19, -2
	s_add_u32 s92, s92, 0x80
	s_addc_u32 s93, s93, 0
	s_add_u32 s96, s94, 0x100
	s_addc_u32 s97, s95, 0
	s_mov_b32 s94, 0
	s_cmp_lt_u32 s59, 2
	s_cbranch_scc1 .Lkloop_zero
	s_add_i32 vcc_lo, s94, 2
	s_add_u32 s82, s92, 0x80
	s_addc_u32 s83, s93, 0
	s_add_i32 vcc_hi, 0, 0x10000
	s_cmp_eq_u32 s34, s94
	s_cselect_b32 s95, s89, s83
	s_cselect_b32 s94, s88, s82
	v_add_u32_e32 v136, vcc_hi, v176
	s_cselect_b32 s83, s91, s97
	s_cselect_b32 s82, s90, s96
	s_add_i32 s7, 0, 0x14000
	s_waitcnt lgkmcnt(0)
	ds_read_b128 v[128:131], v136
	ds_read_b128 v[132:135], v136 offset:1024
	ds_read_b128 v[152:155], v136 offset:2048
	ds_read_b128 v[156:159], v136 offset:3072
	v_add_u32_e32 v136, s7, v176
	ds_read_b128 v[180:183], v136
	ds_read_b128 v[184:187], v136 offset:1024
	ds_read_b128 v[188:191], v136 offset:2048
	ds_read_b128 v[192:195], v136 offset:3072
	v_lshl_add_u64 v[160:161], s[92:93], 0, v[148:149]
	s_add_i32 m0, s52, 0xc000
	ds_read_b128 v[196:199], v178
	ds_read_b128 v[200:203], v178 offset:1024
	ds_read_b128 v[204:207], v178 offset:2048
	ds_read_b128 v[208:211], v178 offset:3072
	ds_read_b128 v[212:215], v178 offset:4096
	ds_read_b128 v[216:219], v178 offset:5120
	ds_read_b128 v[220:223], v178 offset:6144
	ds_read_b128 v[224:227], v178 offset:7168
	global_load_lds_dwordx4 v[160:161], off
	v_lshl_add_u64 v[160:161], s[92:93], 0, v[150:151]
	s_add_i32 m0, s52, 0xe000
	s_nop 0
	global_load_lds_dwordx4 v[160:161], off
	s_waitcnt vmcnt(24)
	s_waitcnt lgkmcnt(0)
	s_barrier
	s_setprio 1
	s_waitcnt lgkmcnt(0)
	v_mfma_f32_16x16x32_bf16 v[124:127], v[128:131], v[196:199], 0
	v_mfma_f32_16x16x32_bf16 v[120:123], v[152:155], v[196:199], 0
	v_mfma_f32_16x16x32_bf16 v[108:111], v[128:131], v[204:207], 0
	v_mfma_f32_16x16x32_bf16 v[104:107], v[152:155], v[204:207], 0
	v_mfma_f32_16x16x32_bf16 v[92:95], v[128:131], v[212:215], 0
	v_mfma_f32_16x16x32_bf16 v[88:91], v[152:155], v[212:215], 0
	v_mfma_f32_16x16x32_bf16 v[76:79], v[128:131], v[220:223], 0
	v_mfma_f32_16x16x32_bf16 v[72:75], v[152:155], v[220:223], 0
	v_mfma_f32_16x16x32_bf16 v[124:127], v[132:135], v[200:203], v[124:127]
	v_mfma_f32_16x16x32_bf16 v[120:123], v[156:159], v[200:203], v[120:123]
	v_mfma_f32_16x16x32_bf16 v[108:111], v[132:135], v[208:211], v[108:111]
	v_mfma_f32_16x16x32_bf16 v[104:107], v[156:159], v[208:211], v[104:107]
	v_mfma_f32_16x16x32_bf16 v[92:95], v[132:135], v[216:219], v[92:95]
	v_mfma_f32_16x16x32_bf16 v[88:91], v[156:159], v[216:219], v[88:91]
	v_mfma_f32_16x16x32_bf16 v[76:79], v[132:135], v[224:227], v[76:79]
	v_mfma_f32_16x16x32_bf16 v[72:75], v[156:159], v[224:227], v[72:75]
	s_setprio 0
	s_setprio 1
	v_mfma_f32_16x16x32_bf16 v[116:119], v[180:183], v[196:199], 0
	v_mfma_f32_16x16x32_bf16 v[112:115], v[188:191], v[196:199], 0
	v_mfma_f32_16x16x32_bf16 v[100:103], v[180:183], v[204:207], 0
	v_mfma_f32_16x16x32_bf16 v[96:99], v[188:191], v[204:207], 0
	v_mfma_f32_16x16x32_bf16 v[84:87], v[180:183], v[212:215], 0
	v_mfma_f32_16x16x32_bf16 v[80:83], v[188:191], v[212:215], 0
	v_mfma_f32_16x16x32_bf16 v[68:71], v[180:183], v[220:223], 0
	v_mfma_f32_16x16x32_bf16 v[64:67], v[188:191], v[220:223], 0
	v_mfma_f32_16x16x32_bf16 v[116:119], v[184:187], v[200:203], v[116:119]
	v_mfma_f32_16x16x32_bf16 v[112:115], v[192:195], v[200:203], v[112:115]
	v_mfma_f32_16x16x32_bf16 v[100:103], v[184:187], v[208:211], v[100:103]
	v_mfma_f32_16x16x32_bf16 v[96:99], v[192:195], v[208:211], v[96:99]
	v_mfma_f32_16x16x32_bf16 v[84:87], v[184:187], v[216:219], v[84:87]
	v_mfma_f32_16x16x32_bf16 v[80:83], v[192:195], v[216:219], v[80:83]
	v_mfma_f32_16x16x32_bf16 v[68:71], v[184:187], v[224:227], v[68:71]
	v_mfma_f32_16x16x32_bf16 v[64:67], v[192:195], v[224:227], v[64:67]
	s_setprio 0
	s_barrier
	s_add_i32 vcc_hi, vcc_hi, s51
	v_lshl_add_u64 v[160:161], s[82:83], 0, v[140:141]
	s_mov_b32 m0, vcc_hi
	ds_read_b128 v[196:199], v178 offset:16384
	ds_read_b128 v[200:203], v178 offset:17408
	ds_read_b128 v[204:207], v178 offset:18432
	ds_read_b128 v[208:211], v178 offset:19456
	ds_read_b128 v[212:215], v178 offset:20480
	ds_read_b128 v[216:219], v178 offset:21504
	ds_read_b128 v[220:223], v178 offset:22528
	ds_read_b128 v[224:227], v178 offset:23552
	global_load_lds_dwordx4 v[160:161], off
	s_add_i32 m0, vcc_hi, 0x2000
	v_lshl_add_u64 v[228:229], s[82:83], 0, v[144:145]
	s_add_u32 s82, s82, s2
	s_addc_u32 s83, s83, s3
	s_add_i32 s7, s7, s51
	global_load_lds_dwordx4 v[228:229], off
	v_lshl_add_u64 v[230:231], s[82:83], 0, v[140:141]
	s_mov_b32 m0, s7
	v_lshl_add_u64 v[232:233], s[82:83], 0, v[144:145]
	global_load_lds_dwordx4 v[230:231], off
	s_add_i32 m0, s7, 0x2000
	v_lshl_add_u64 v[234:235], s[94:95], 0, v[138:139]
	global_load_lds_dwordx4 v[232:233], off
	s_mov_b32 m0, s52
	v_lshl_add_u64 v[236:237], s[94:95], 0, v[142:143]
	global_load_lds_dwordx4 v[234:235], off
	s_mov_b32 m0, s53
	s_nop 0
	global_load_lds_dwordx4 v[236:237], off
	s_waitcnt vmcnt(24)
	s_waitcnt lgkmcnt(0)
	s_barrier
	s_setprio 1
	s_waitcnt lgkmcnt(0)
	v_mfma_f32_16x16x32_bf16 v[60:63], v[128:131], v[196:199], 0
	v_mfma_f32_16x16x32_bf16 v[56:59], v[152:155], v[196:199], 0
	v_mfma_f32_16x16x32_bf16 v[44:47], v[128:131], v[204:207], 0
	v_mfma_f32_16x16x32_bf16 v[40:43], v[152:155], v[204:207], 0
	v_mfma_f32_16x16x32_bf16 v[28:31], v[128:131], v[212:215], 0
	v_mfma_f32_16x16x32_bf16 v[24:27], v[152:155], v[212:215], 0
	v_mfma_f32_16x16x32_bf16 v[12:15], v[128:131], v[220:223], 0
	v_mfma_f32_16x16x32_bf16 v[8:11], v[152:155], v[220:223], 0
	v_mfma_f32_16x16x32_bf16 v[60:63], v[132:135], v[200:203], v[60:63]
	v_mfma_f32_16x16x32_bf16 v[56:59], v[156:159], v[200:203], v[56:59]
	v_mfma_f32_16x16x32_bf16 v[44:47], v[132:135], v[208:211], v[44:47]
	v_mfma_f32_16x16x32_bf16 v[40:43], v[156:159], v[208:211], v[40:43]
	v_mfma_f32_16x16x32_bf16 v[28:31], v[132:135], v[216:219], v[28:31]
	v_mfma_f32_16x16x32_bf16 v[24:27], v[156:159], v[216:219], v[24:27]
	v_mfma_f32_16x16x32_bf16 v[12:15], v[132:135], v[224:227], v[12:15]
	v_mfma_f32_16x16x32_bf16 v[8:11], v[156:159], v[224:227], v[8:11]
	s_setprio 0
	s_setprio 1
	v_mfma_f32_16x16x32_bf16 v[52:55], v[180:183], v[196:199], 0
	v_mfma_f32_16x16x32_bf16 v[48:51], v[188:191], v[196:199], 0
	v_mfma_f32_16x16x32_bf16 v[36:39], v[180:183], v[204:207], 0
	v_mfma_f32_16x16x32_bf16 v[32:35], v[188:191], v[204:207], 0
	v_mfma_f32_16x16x32_bf16 v[20:23], v[180:183], v[212:215], 0
	v_mfma_f32_16x16x32_bf16 v[16:19], v[188:191], v[212:215], 0
	v_mfma_f32_16x16x32_bf16 v[4:7], v[180:183], v[220:223], 0
	v_mfma_f32_16x16x32_bf16 v[0:3], v[188:191], v[220:223], 0
	v_mfma_f32_16x16x32_bf16 v[52:55], v[184:187], v[200:203], v[52:55]
	v_mfma_f32_16x16x32_bf16 v[48:51], v[192:195], v[200:203], v[48:51]
	v_mfma_f32_16x16x32_bf16 v[36:39], v[184:187], v[208:211], v[36:39]
	v_mfma_f32_16x16x32_bf16 v[32:35], v[192:195], v[208:211], v[32:35]
	v_mfma_f32_16x16x32_bf16 v[20:23], v[184:187], v[216:219], v[20:23]
	v_mfma_f32_16x16x32_bf16 v[16:19], v[192:195], v[216:219], v[16:19]
	v_mfma_f32_16x16x32_bf16 v[4:7], v[184:187], v[224:227], v[4:7]
	v_mfma_f32_16x16x32_bf16 v[0:3], v[192:195], v[224:227], v[0:3]
	s_setprio 0
	s_barrier
	s_add_i32 s7, 0, 0x18000
	v_add_u32_e32 v136, s7, v176
	s_add_i32 vcc_hi, 0, 0x1c000
	ds_read_b128 v[128:131], v136
	ds_read_b128 v[132:135], v136 offset:1024
	ds_read_b128 v[152:155], v136 offset:2048
	ds_read_b128 v[156:159], v136 offset:3072
	v_add_u32_e32 v136, vcc_hi, v176
	ds_read_b128 v[180:183], v136
	ds_read_b128 v[184:187], v136 offset:1024
	ds_read_b128 v[188:191], v136 offset:2048
	ds_read_b128 v[192:195], v136 offset:3072
	s_add_u32 s82, s94, s2
	s_addc_u32 s83, s95, s3
	s_mov_b32 m0, s54
	v_lshl_add_u64 v[238:239], s[82:83], 0, v[138:139]
	ds_read_b128 v[196:199], v178 offset:32768
	ds_read_b128 v[200:203], v178 offset:33792
	ds_read_b128 v[204:207], v178 offset:34816
	ds_read_b128 v[208:211], v178 offset:35840
	ds_read_b128 v[212:215], v178 offset:36864
	ds_read_b128 v[216:219], v178 offset:37888
	ds_read_b128 v[220:223], v178 offset:38912
	ds_read_b128 v[224:227], v178 offset:39936
	global_load_lds_dwordx4 v[238:239], off
	v_lshl_add_u64 v[238:239], s[82:83], 0, v[142:143]
	s_mov_b32 m0, s55
	s_nop 0
	global_load_lds_dwordx4 v[238:239], off
	s_waitcnt vmcnt(8)
	s_waitcnt lgkmcnt(0)
	s_barrier
	s_setprio 1
	s_waitcnt lgkmcnt(0)
	v_mfma_f32_16x16x32_bf16 v[124:127], v[128:131], v[196:199], v[124:127]
	v_mfma_f32_16x16x32_bf16 v[120:123], v[152:155], v[196:199], v[120:123]
	v_mfma_f32_16x16x32_bf16 v[108:111], v[128:131], v[204:207], v[108:111]
	v_mfma_f32_16x16x32_bf16 v[104:107], v[152:155], v[204:207], v[104:107]
	v_mfma_f32_16x16x32_bf16 v[92:95], v[128:131], v[212:215], v[92:95]
	v_mfma_f32_16x16x32_bf16 v[88:91], v[152:155], v[212:215], v[88:91]
	v_mfma_f32_16x16x32_bf16 v[76:79], v[128:131], v[220:223], v[76:79]
	v_mfma_f32_16x16x32_bf16 v[72:75], v[152:155], v[220:223], v[72:75]
	v_mfma_f32_16x16x32_bf16 v[124:127], v[132:135], v[200:203], v[124:127]
	v_mfma_f32_16x16x32_bf16 v[120:123], v[156:159], v[200:203], v[120:123]
	v_mfma_f32_16x16x32_bf16 v[108:111], v[132:135], v[208:211], v[108:111]
	v_mfma_f32_16x16x32_bf16 v[104:107], v[156:159], v[208:211], v[104:107]
	v_mfma_f32_16x16x32_bf16 v[92:95], v[132:135], v[216:219], v[92:95]
	v_mfma_f32_16x16x32_bf16 v[88:91], v[156:159], v[216:219], v[88:91]
	v_mfma_f32_16x16x32_bf16 v[76:79], v[132:135], v[224:227], v[76:79]
	v_mfma_f32_16x16x32_bf16 v[72:75], v[156:159], v[224:227], v[72:75]
	s_setprio 0
	s_setprio 1
	v_mfma_f32_16x16x32_bf16 v[116:119], v[180:183], v[196:199], v[116:119]
	v_mfma_f32_16x16x32_bf16 v[112:115], v[188:191], v[196:199], v[112:115]
	v_mfma_f32_16x16x32_bf16 v[100:103], v[180:183], v[204:207], v[100:103]
	v_mfma_f32_16x16x32_bf16 v[96:99], v[188:191], v[204:207], v[96:99]
	v_mfma_f32_16x16x32_bf16 v[84:87], v[180:183], v[212:215], v[84:87]
	v_mfma_f32_16x16x32_bf16 v[80:83], v[188:191], v[212:215], v[80:83]
	v_mfma_f32_16x16x32_bf16 v[68:71], v[180:183], v[220:223], v[68:71]
	v_mfma_f32_16x16x32_bf16 v[64:67], v[188:191], v[220:223], v[64:67]
	v_mfma_f32_16x16x32_bf16 v[116:119], v[184:187], v[200:203], v[116:119]
	v_mfma_f32_16x16x32_bf16 v[112:115], v[192:195], v[200:203], v[112:115]
	v_mfma_f32_16x16x32_bf16 v[100:103], v[184:187], v[208:211], v[100:103]
	v_mfma_f32_16x16x32_bf16 v[96:99], v[192:195], v[208:211], v[96:99]
	v_mfma_f32_16x16x32_bf16 v[84:87], v[184:187], v[216:219], v[84:87]
	v_mfma_f32_16x16x32_bf16 v[80:83], v[192:195], v[216:219], v[80:83]
	v_mfma_f32_16x16x32_bf16 v[68:71], v[184:187], v[224:227], v[68:71]
	v_mfma_f32_16x16x32_bf16 v[64:67], v[192:195], v[224:227], v[64:67]
	s_setprio 0
	s_barrier
	s_add_i32 s7, s7, s51
	v_lshl_add_u64 v[160:161], v[160:161], 0, s[26:27]
	s_mov_b32 m0, s7
	ds_read_b128 v[196:199], v178 offset:49152
	ds_read_b128 v[200:203], v178 offset:50176
	ds_read_b128 v[204:207], v178 offset:51200
	ds_read_b128 v[208:211], v178 offset:52224
	ds_read_b128 v[212:215], v178 offset:53248
	ds_read_b128 v[216:219], v178 offset:54272
	ds_read_b128 v[220:223], v178 offset:55296
	ds_read_b128 v[224:227], v178 offset:56320
	global_load_lds_dwordx4 v[160:161], off
	v_lshl_add_u64 v[160:161], v[228:229], 0, s[26:27]
	s_add_i32 m0, s7, 0x2000
	s_add_i32 s7, vcc_hi, s51
	global_load_lds_dwordx4 v[160:161], off
	v_lshl_add_u64 v[160:161], v[230:231], 0, s[26:27]
	s_mov_b32 m0, s7
	s_nop 0
	global_load_lds_dwordx4 v[160:161], off
	v_lshl_add_u64 v[160:161], v[232:233], 0, s[26:27]
	s_add_i32 m0, s7, 0x2000
	s_nop 0
	global_load_lds_dwordx4 v[160:161], off
	v_lshl_add_u64 v[160:161], v[234:235], 0, s[26:27]
	s_mov_b32 m0, s57
	s_nop 0
	global_load_lds_dwordx4 v[160:161], off
	v_lshl_add_u64 v[160:161], v[236:237], 0, s[26:27]
	s_mov_b32 m0, s58
	s_nop 0
	global_load_lds_dwordx4 v[160:161], off
	s_waitcnt vmcnt(8)
	s_waitcnt lgkmcnt(0)
	s_barrier
	s_setprio 1
	s_waitcnt lgkmcnt(0)
	v_mfma_f32_16x16x32_bf16 v[60:63], v[128:131], v[196:199], v[60:63]
	v_mfma_f32_16x16x32_bf16 v[56:59], v[152:155], v[196:199], v[56:59]
	v_mfma_f32_16x16x32_bf16 v[44:47], v[128:131], v[204:207], v[44:47]
	v_mfma_f32_16x16x32_bf16 v[40:43], v[152:155], v[204:207], v[40:43]
	v_mfma_f32_16x16x32_bf16 v[28:31], v[128:131], v[212:215], v[28:31]
	v_mfma_f32_16x16x32_bf16 v[24:27], v[152:155], v[212:215], v[24:27]
	v_mfma_f32_16x16x32_bf16 v[12:15], v[128:131], v[220:223], v[12:15]
	v_mfma_f32_16x16x32_bf16 v[8:11], v[152:155], v[220:223], v[8:11]
	v_mfma_f32_16x16x32_bf16 v[60:63], v[132:135], v[200:203], v[60:63]
	v_mfma_f32_16x16x32_bf16 v[56:59], v[156:159], v[200:203], v[56:59]
	v_mfma_f32_16x16x32_bf16 v[44:47], v[132:135], v[208:211], v[44:47]
	v_mfma_f32_16x16x32_bf16 v[40:43], v[156:159], v[208:211], v[40:43]
	v_mfma_f32_16x16x32_bf16 v[28:31], v[132:135], v[216:219], v[28:31]
	v_mfma_f32_16x16x32_bf16 v[24:27], v[156:159], v[216:219], v[24:27]
	v_mfma_f32_16x16x32_bf16 v[12:15], v[132:135], v[224:227], v[12:15]
	v_mfma_f32_16x16x32_bf16 v[8:11], v[156:159], v[224:227], v[8:11]
	s_setprio 0
	s_setprio 1
	v_mfma_f32_16x16x32_bf16 v[52:55], v[180:183], v[196:199], v[52:55]
	v_mfma_f32_16x16x32_bf16 v[48:51], v[188:191], v[196:199], v[48:51]
	v_mfma_f32_16x16x32_bf16 v[36:39], v[180:183], v[204:207], v[36:39]
	v_mfma_f32_16x16x32_bf16 v[32:35], v[188:191], v[204:207], v[32:35]
	v_mfma_f32_16x16x32_bf16 v[20:23], v[180:183], v[212:215], v[20:23]
	v_mfma_f32_16x16x32_bf16 v[16:19], v[188:191], v[212:215], v[16:19]
	v_mfma_f32_16x16x32_bf16 v[4:7], v[180:183], v[220:223], v[4:7]
	v_mfma_f32_16x16x32_bf16 v[0:3], v[188:191], v[220:223], v[0:3]
	v_mfma_f32_16x16x32_bf16 v[52:55], v[184:187], v[200:203], v[52:55]
	v_mfma_f32_16x16x32_bf16 v[48:51], v[192:195], v[200:203], v[48:51]
	v_mfma_f32_16x16x32_bf16 v[36:39], v[184:187], v[208:211], v[36:39]
	v_mfma_f32_16x16x32_bf16 v[32:35], v[192:195], v[208:211], v[32:35]
	v_mfma_f32_16x16x32_bf16 v[20:23], v[184:187], v[216:219], v[20:23]
	v_mfma_f32_16x16x32_bf16 v[16:19], v[192:195], v[216:219], v[16:19]
	v_mfma_f32_16x16x32_bf16 v[4:7], v[184:187], v[224:227], v[4:7]
	v_mfma_f32_16x16x32_bf16 v[0:3], v[192:195], v[224:227], v[0:3]
	s_setprio 0
	s_add_u32 s92, s92, 0x100
	s_addc_u32 s93, s93, 0
	s_add_u32 s96, s96, 0x100
	s_addc_u32 s97, s97, 0
	s_barrier
	s_cmp_ge_u32 vcc_lo, s19
	s_mov_b32 s94, vcc_lo
	s_cbranch_scc0 .LBB0_150
	s_branch .Lkloop_done

.LBB0_150:
	s_add_i32 vcc_lo, s94, 2
	s_add_u32 s82, s92, 0x80
	s_addc_u32 s83, s93, 0
	s_add_i32 vcc_hi, 0, 0x10000
	s_cmp_eq_u32 s34, s94
	s_cselect_b32 s95, s89, s83
	s_cselect_b32 s94, s88, s82
	v_add_u32_e32 v136, vcc_hi, v176
	s_cselect_b32 s83, s91, s97
	s_cselect_b32 s82, s90, s96
	s_add_i32 s7, 0, 0x14000
	s_waitcnt lgkmcnt(0)
	ds_read_b128 v[128:131], v136
	ds_read_b128 v[132:135], v136 offset:1024
	ds_read_b128 v[152:155], v136 offset:2048
	ds_read_b128 v[156:159], v136 offset:3072
	v_add_u32_e32 v136, s7, v176
	ds_read_b128 v[180:183], v136
	ds_read_b128 v[184:187], v136 offset:1024
	ds_read_b128 v[188:191], v136 offset:2048
	ds_read_b128 v[192:195], v136 offset:3072
	v_lshl_add_u64 v[160:161], s[92:93], 0, v[148:149]
	s_add_i32 m0, s52, 0xc000
	ds_read_b128 v[196:199], v178
	ds_read_b128 v[200:203], v178 offset:1024
	ds_read_b128 v[204:207], v178 offset:2048
	ds_read_b128 v[208:211], v178 offset:3072
	ds_read_b128 v[212:215], v178 offset:4096
	ds_read_b128 v[216:219], v178 offset:5120
	ds_read_b128 v[220:223], v178 offset:6144
	ds_read_b128 v[224:227], v178 offset:7168
	global_load_lds_dwordx4 v[160:161], off
	v_lshl_add_u64 v[160:161], s[92:93], 0, v[150:151]
	s_add_i32 m0, s52, 0xe000
	s_nop 0
	global_load_lds_dwordx4 v[160:161], off
	s_waitcnt vmcnt(8)
	s_waitcnt lgkmcnt(0)
	s_barrier
	s_setprio 1
	s_waitcnt lgkmcnt(0)
	v_mfma_f32_16x16x32_bf16 v[124:127], v[128:131], v[196:199], v[124:127]
	v_mfma_f32_16x16x32_bf16 v[120:123], v[152:155], v[196:199], v[120:123]
	v_mfma_f32_16x16x32_bf16 v[108:111], v[128:131], v[204:207], v[108:111]
	v_mfma_f32_16x16x32_bf16 v[104:107], v[152:155], v[204:207], v[104:107]
	v_mfma_f32_16x16x32_bf16 v[92:95], v[128:131], v[212:215], v[92:95]
	v_mfma_f32_16x16x32_bf16 v[88:91], v[152:155], v[212:215], v[88:91]
	v_mfma_f32_16x16x32_bf16 v[76:79], v[128:131], v[220:223], v[76:79]
	v_mfma_f32_16x16x32_bf16 v[72:75], v[152:155], v[220:223], v[72:75]
	v_mfma_f32_16x16x32_bf16 v[124:127], v[132:135], v[200:203], v[124:127]
	v_mfma_f32_16x16x32_bf16 v[120:123], v[156:159], v[200:203], v[120:123]
	v_mfma_f32_16x16x32_bf16 v[108:111], v[132:135], v[208:211], v[108:111]
	v_mfma_f32_16x16x32_bf16 v[104:107], v[156:159], v[208:211], v[104:107]
	v_mfma_f32_16x16x32_bf16 v[92:95], v[132:135], v[216:219], v[92:95]
	v_mfma_f32_16x16x32_bf16 v[88:91], v[156:159], v[216:219], v[88:91]
	v_mfma_f32_16x16x32_bf16 v[76:79], v[132:135], v[224:227], v[76:79]
	v_mfma_f32_16x16x32_bf16 v[72:75], v[156:159], v[224:227], v[72:75]
	s_setprio 0
	s_setprio 1
	v_mfma_f32_16x16x32_bf16 v[116:119], v[180:183], v[196:199], v[116:119]
	v_mfma_f32_16x16x32_bf16 v[112:115], v[188:191], v[196:199], v[112:115]
	v_mfma_f32_16x16x32_bf16 v[100:103], v[180:183], v[204:207], v[100:103]
	v_mfma_f32_16x16x32_bf16 v[96:99], v[188:191], v[204:207], v[96:99]
	v_mfma_f32_16x16x32_bf16 v[84:87], v[180:183], v[212:215], v[84:87]
	v_mfma_f32_16x16x32_bf16 v[80:83], v[188:191], v[212:215], v[80:83]
	v_mfma_f32_16x16x32_bf16 v[68:71], v[180:183], v[220:223], v[68:71]
	v_mfma_f32_16x16x32_bf16 v[64:67], v[188:191], v[220:223], v[64:67]
	v_mfma_f32_16x16x32_bf16 v[116:119], v[184:187], v[200:203], v[116:119]
	v_mfma_f32_16x16x32_bf16 v[112:115], v[192:195], v[200:203], v[112:115]
	v_mfma_f32_16x16x32_bf16 v[100:103], v[184:187], v[208:211], v[100:103]
	v_mfma_f32_16x16x32_bf16 v[96:99], v[192:195], v[208:211], v[96:99]
	v_mfma_f32_16x16x32_bf16 v[84:87], v[184:187], v[216:219], v[84:87]
	v_mfma_f32_16x16x32_bf16 v[80:83], v[192:195], v[216:219], v[80:83]
	v_mfma_f32_16x16x32_bf16 v[68:71], v[184:187], v[224:227], v[68:71]
	v_mfma_f32_16x16x32_bf16 v[64:67], v[192:195], v[224:227], v[64:67]
	s_setprio 0
	s_barrier
	s_add_i32 vcc_hi, vcc_hi, s51
	v_lshl_add_u64 v[160:161], s[82:83], 0, v[140:141]
	s_mov_b32 m0, vcc_hi
	ds_read_b128 v[196:199], v178 offset:16384
	ds_read_b128 v[200:203], v178 offset:17408
	ds_read_b128 v[204:207], v178 offset:18432
	ds_read_b128 v[208:211], v178 offset:19456
	ds_read_b128 v[212:215], v178 offset:20480
	ds_read_b128 v[216:219], v178 offset:21504
	ds_read_b128 v[220:223], v178 offset:22528
	ds_read_b128 v[224:227], v178 offset:23552
	global_load_lds_dwordx4 v[160:161], off
	s_add_i32 m0, vcc_hi, 0x2000
	v_lshl_add_u64 v[228:229], s[82:83], 0, v[144:145]
	s_add_u32 s82, s82, s2
	s_addc_u32 s83, s83, s3
	s_add_i32 s7, s7, s51
	global_load_lds_dwordx4 v[228:229], off
	v_lshl_add_u64 v[230:231], s[82:83], 0, v[140:141]
	s_mov_b32 m0, s7
	v_lshl_add_u64 v[232:233], s[82:83], 0, v[144:145]
	global_load_lds_dwordx4 v[230:231], off
	s_add_i32 m0, s7, 0x2000
	v_lshl_add_u64 v[234:235], s[94:95], 0, v[138:139]
	global_load_lds_dwordx4 v[232:233], off
	s_mov_b32 m0, s52
	v_lshl_add_u64 v[236:237], s[94:95], 0, v[142:143]
	global_load_lds_dwordx4 v[234:235], off
	s_mov_b32 m0, s53
	s_nop 0
	global_load_lds_dwordx4 v[236:237], off
	s_waitcnt vmcnt(8)
	s_waitcnt lgkmcnt(0)
	s_barrier
	s_setprio 1
	s_waitcnt lgkmcnt(0)
	v_mfma_f32_16x16x32_bf16 v[60:63], v[128:131], v[196:199], v[60:63]
	v_mfma_f32_16x16x32_bf16 v[56:59], v[152:155], v[196:199], v[56:59]
	v_mfma_f32_16x16x32_bf16 v[44:47], v[128:131], v[204:207], v[44:47]
	v_mfma_f32_16x16x32_bf16 v[40:43], v[152:155], v[204:207], v[40:43]
	v_mfma_f32_16x16x32_bf16 v[28:31], v[128:131], v[212:215], v[28:31]
	v_mfma_f32_16x16x32_bf16 v[24:27], v[152:155], v[212:215], v[24:27]
	v_mfma_f32_16x16x32_bf16 v[12:15], v[128:131], v[220:223], v[12:15]
	v_mfma_f32_16x16x32_bf16 v[8:11], v[152:155], v[220:223], v[8:11]
	v_mfma_f32_16x16x32_bf16 v[60:63], v[132:135], v[200:203], v[60:63]
	v_mfma_f32_16x16x32_bf16 v[56:59], v[156:159], v[200:203], v[56:59]
	v_mfma_f32_16x16x32_bf16 v[44:47], v[132:135], v[208:211], v[44:47]
	v_mfma_f32_16x16x32_bf16 v[40:43], v[156:159], v[208:211], v[40:43]
	v_mfma_f32_16x16x32_bf16 v[28:31], v[132:135], v[216:219], v[28:31]
	v_mfma_f32_16x16x32_bf16 v[24:27], v[156:159], v[216:219], v[24:27]
	v_mfma_f32_16x16x32_bf16 v[12:15], v[132:135], v[224:227], v[12:15]
	v_mfma_f32_16x16x32_bf16 v[8:11], v[156:159], v[224:227], v[8:11]
	s_setprio 0
	s_setprio 1
	v_mfma_f32_16x16x32_bf16 v[52:55], v[180:183], v[196:199], v[52:55]
	v_mfma_f32_16x16x32_bf16 v[48:51], v[188:191], v[196:199], v[48:51]
	v_mfma_f32_16x16x32_bf16 v[36:39], v[180:183], v[204:207], v[36:39]
	v_mfma_f32_16x16x32_bf16 v[32:35], v[188:191], v[204:207], v[32:35]
	v_mfma_f32_16x16x32_bf16 v[20:23], v[180:183], v[212:215], v[20:23]
	v_mfma_f32_16x16x32_bf16 v[16:19], v[188:191], v[212:215], v[16:19]
	v_mfma_f32_16x16x32_bf16 v[4:7], v[180:183], v[220:223], v[4:7]
	v_mfma_f32_16x16x32_bf16 v[0:3], v[188:191], v[220:223], v[0:3]
	v_mfma_f32_16x16x32_bf16 v[52:55], v[184:187], v[200:203], v[52:55]
	v_mfma_f32_16x16x32_bf16 v[48:51], v[192:195], v[200:203], v[48:51]
	v_mfma_f32_16x16x32_bf16 v[36:39], v[184:187], v[208:211], v[36:39]
	v_mfma_f32_16x16x32_bf16 v[32:35], v[192:195], v[208:211], v[32:35]
	v_mfma_f32_16x16x32_bf16 v[20:23], v[184:187], v[216:219], v[20:23]
	v_mfma_f32_16x16x32_bf16 v[16:19], v[192:195], v[216:219], v[16:19]
	v_mfma_f32_16x16x32_bf16 v[4:7], v[184:187], v[224:227], v[4:7]
	v_mfma_f32_16x16x32_bf16 v[0:3], v[192:195], v[224:227], v[0:3]
	s_setprio 0
	s_barrier
	s_add_i32 s7, 0, 0x18000
	v_add_u32_e32 v136, s7, v176
	s_add_i32 vcc_hi, 0, 0x1c000
	ds_read_b128 v[128:131], v136
	ds_read_b128 v[132:135], v136 offset:1024
	ds_read_b128 v[152:155], v136 offset:2048
	ds_read_b128 v[156:159], v136 offset:3072
	v_add_u32_e32 v136, vcc_hi, v176
	ds_read_b128 v[180:183], v136
	ds_read_b128 v[184:187], v136 offset:1024
	ds_read_b128 v[188:191], v136 offset:2048
	ds_read_b128 v[192:195], v136 offset:3072
	s_add_u32 s82, s94, s2
	s_addc_u32 s83, s95, s3
	s_mov_b32 m0, s54
	v_lshl_add_u64 v[238:239], s[82:83], 0, v[138:139]
	ds_read_b128 v[196:199], v178 offset:32768
	ds_read_b128 v[200:203], v178 offset:33792
	ds_read_b128 v[204:207], v178 offset:34816
	ds_read_b128 v[208:211], v178 offset:35840
	ds_read_b128 v[212:215], v178 offset:36864
	ds_read_b128 v[216:219], v178 offset:37888
	ds_read_b128 v[220:223], v178 offset:38912
	ds_read_b128 v[224:227], v178 offset:39936
	global_load_lds_dwordx4 v[238:239], off
	v_lshl_add_u64 v[238:239], s[82:83], 0, v[142:143]
	s_mov_b32 m0, s55
	s_nop 0
	global_load_lds_dwordx4 v[238:239], off
	s_waitcnt vmcnt(8)
	s_waitcnt lgkmcnt(0)
	s_barrier
	s_setprio 1
	s_waitcnt lgkmcnt(0)
	v_mfma_f32_16x16x32_bf16 v[124:127], v[128:131], v[196:199], v[124:127]
	v_mfma_f32_16x16x32_bf16 v[120:123], v[152:155], v[196:199], v[120:123]
	v_mfma_f32_16x16x32_bf16 v[108:111], v[128:131], v[204:207], v[108:111]
	v_mfma_f32_16x16x32_bf16 v[104:107], v[152:155], v[204:207], v[104:107]
	v_mfma_f32_16x16x32_bf16 v[92:95], v[128:131], v[212:215], v[92:95]
	v_mfma_f32_16x16x32_bf16 v[88:91], v[152:155], v[212:215], v[88:91]
	v_mfma_f32_16x16x32_bf16 v[76:79], v[128:131], v[220:223], v[76:79]
	v_mfma_f32_16x16x32_bf16 v[72:75], v[152:155], v[220:223], v[72:75]
	v_mfma_f32_16x16x32_bf16 v[124:127], v[132:135], v[200:203], v[124:127]
	v_mfma_f32_16x16x32_bf16 v[120:123], v[156:159], v[200:203], v[120:123]
	v_mfma_f32_16x16x32_bf16 v[108:111], v[132:135], v[208:211], v[108:111]
	v_mfma_f32_16x16x32_bf16 v[104:107], v[156:159], v[208:211], v[104:107]
	v_mfma_f32_16x16x32_bf16 v[92:95], v[132:135], v[216:219], v[92:95]
	v_mfma_f32_16x16x32_bf16 v[88:91], v[156:159], v[216:219], v[88:91]
	v_mfma_f32_16x16x32_bf16 v[76:79], v[132:135], v[224:227], v[76:79]
	v_mfma_f32_16x16x32_bf16 v[72:75], v[156:159], v[224:227], v[72:75]
	s_setprio 0
	s_setprio 1
	v_mfma_f32_16x16x32_bf16 v[116:119], v[180:183], v[196:199], v[116:119]
	v_mfma_f32_16x16x32_bf16 v[112:115], v[188:191], v[196:199], v[112:115]
	v_mfma_f32_16x16x32_bf16 v[100:103], v[180:183], v[204:207], v[100:103]
	v_mfma_f32_16x16x32_bf16 v[96:99], v[188:191], v[204:207], v[96:99]
	v_mfma_f32_16x16x32_bf16 v[84:87], v[180:183], v[212:215], v[84:87]
	v_mfma_f32_16x16x32_bf16 v[80:83], v[188:191], v[212:215], v[80:83]
	v_mfma_f32_16x16x32_bf16 v[68:71], v[180:183], v[220:223], v[68:71]
	v_mfma_f32_16x16x32_bf16 v[64:67], v[188:191], v[220:223], v[64:67]
	v_mfma_f32_16x16x32_bf16 v[116:119], v[184:187], v[200:203], v[116:119]
	v_mfma_f32_16x16x32_bf16 v[112:115], v[192:195], v[200:203], v[112:115]
	v_mfma_f32_16x16x32_bf16 v[100:103], v[184:187], v[208:211], v[100:103]
	v_mfma_f32_16x16x32_bf16 v[96:99], v[192:195], v[208:211], v[96:99]
	v_mfma_f32_16x16x32_bf16 v[84:87], v[184:187], v[216:219], v[84:87]
	v_mfma_f32_16x16x32_bf16 v[80:83], v[192:195], v[216:219], v[80:83]
	v_mfma_f32_16x16x32_bf16 v[68:71], v[184:187], v[224:227], v[68:71]
	v_mfma_f32_16x16x32_bf16 v[64:67], v[192:195], v[224:227], v[64:67]
	s_setprio 0
	s_barrier
	s_add_i32 s7, s7, s51
	v_lshl_add_u64 v[160:161], v[160:161], 0, s[26:27]
	s_mov_b32 m0, s7
	ds_read_b128 v[196:199], v178 offset:49152
	ds_read_b128 v[200:203], v178 offset:50176
	ds_read_b128 v[204:207], v178 offset:51200
	ds_read_b128 v[208:211], v178 offset:52224
	ds_read_b128 v[212:215], v178 offset:53248
	ds_read_b128 v[216:219], v178 offset:54272
	ds_read_b128 v[220:223], v178 offset:55296
	ds_read_b128 v[224:227], v178 offset:56320
	global_load_lds_dwordx4 v[160:161], off
	v_lshl_add_u64 v[160:161], v[228:229], 0, s[26:27]
	s_add_i32 m0, s7, 0x2000
	s_add_i32 s7, vcc_hi, s51
	global_load_lds_dwordx4 v[160:161], off
	v_lshl_add_u64 v[160:161], v[230:231], 0, s[26:27]
	s_mov_b32 m0, s7
	s_nop 0
	global_load_lds_dwordx4 v[160:161], off
	v_lshl_add_u64 v[160:161], v[232:233], 0, s[26:27]
	s_add_i32 m0, s7, 0x2000
	s_nop 0
	global_load_lds_dwordx4 v[160:161], off
	v_lshl_add_u64 v[160:161], v[234:235], 0, s[26:27]
	s_mov_b32 m0, s57
	s_nop 0
	global_load_lds_dwordx4 v[160:161], off
	v_lshl_add_u64 v[160:161], v[236:237], 0, s[26:27]
	s_mov_b32 m0, s58
	s_nop 0
	global_load_lds_dwordx4 v[160:161], off
	s_waitcnt vmcnt(8)
	s_waitcnt lgkmcnt(0)
	s_barrier
	s_setprio 1
	s_waitcnt lgkmcnt(0)
	v_mfma_f32_16x16x32_bf16 v[60:63], v[128:131], v[196:199], v[60:63]
	v_mfma_f32_16x16x32_bf16 v[56:59], v[152:155], v[196:199], v[56:59]
	v_mfma_f32_16x16x32_bf16 v[44:47], v[128:131], v[204:207], v[44:47]
	v_mfma_f32_16x16x32_bf16 v[40:43], v[152:155], v[204:207], v[40:43]
	v_mfma_f32_16x16x32_bf16 v[28:31], v[128:131], v[212:215], v[28:31]
	v_mfma_f32_16x16x32_bf16 v[24:27], v[152:155], v[212:215], v[24:27]
	v_mfma_f32_16x16x32_bf16 v[12:15], v[128:131], v[220:223], v[12:15]
	v_mfma_f32_16x16x32_bf16 v[8:11], v[152:155], v[220:223], v[8:11]
	v_mfma_f32_16x16x32_bf16 v[60:63], v[132:135], v[200:203], v[60:63]
	v_mfma_f32_16x16x32_bf16 v[56:59], v[156:159], v[200:203], v[56:59]
	v_mfma_f32_16x16x32_bf16 v[44:47], v[132:135], v[208:211], v[44:47]
	v_mfma_f32_16x16x32_bf16 v[40:43], v[156:159], v[208:211], v[40:43]
	v_mfma_f32_16x16x32_bf16 v[28:31], v[132:135], v[216:219], v[28:31]
	v_mfma_f32_16x16x32_bf16 v[24:27], v[156:159], v[216:219], v[24:27]
	v_mfma_f32_16x16x32_bf16 v[12:15], v[132:135], v[224:227], v[12:15]
	v_mfma_f32_16x16x32_bf16 v[8:11], v[156:159], v[224:227], v[8:11]
	s_setprio 0
	s_setprio 1
	v_mfma_f32_16x16x32_bf16 v[52:55], v[180:183], v[196:199], v[52:55]
	v_mfma_f32_16x16x32_bf16 v[48:51], v[188:191], v[196:199], v[48:51]
	v_mfma_f32_16x16x32_bf16 v[36:39], v[180:183], v[204:207], v[36:39]
	v_mfma_f32_16x16x32_bf16 v[32:35], v[188:191], v[204:207], v[32:35]
	v_mfma_f32_16x16x32_bf16 v[20:23], v[180:183], v[212:215], v[20:23]
	v_mfma_f32_16x16x32_bf16 v[16:19], v[188:191], v[212:215], v[16:19]
	v_mfma_f32_16x16x32_bf16 v[4:7], v[180:183], v[220:223], v[4:7]
	v_mfma_f32_16x16x32_bf16 v[0:3], v[188:191], v[220:223], v[0:3]
	v_mfma_f32_16x16x32_bf16 v[52:55], v[184:187], v[200:203], v[52:55]
	v_mfma_f32_16x16x32_bf16 v[48:51], v[192:195], v[200:203], v[48:51]
	v_mfma_f32_16x16x32_bf16 v[36:39], v[184:187], v[208:211], v[36:39]
	v_mfma_f32_16x16x32_bf16 v[32:35], v[192:195], v[208:211], v[32:35]
	v_mfma_f32_16x16x32_bf16 v[20:23], v[184:187], v[216:219], v[20:23]
	v_mfma_f32_16x16x32_bf16 v[16:19], v[192:195], v[216:219], v[16:19]
	v_mfma_f32_16x16x32_bf16 v[4:7], v[184:187], v[224:227], v[4:7]
	v_mfma_f32_16x16x32_bf16 v[0:3], v[192:195], v[224:227], v[0:3]
	s_setprio 0
	s_add_u32 s92, s92, 0x100
	s_addc_u32 s93, s93, 0
	s_add_u32 s96, s96, 0x100
	s_addc_u32 s97, s97, 0
	s_barrier
	s_cmp_ge_u32 vcc_lo, s19
	s_mov_b32 s94, vcc_lo
	s_cbranch_scc0 .LBB0_150
